# consumer loop: incremental store pointer, hoisted slot addressing, o-chain interleaved with next x-chain
# speedup vs baseline: 1.0184x; 1.0184x over previous
; #define LAS3 __attribute__((address_space(3)))
; DEV void rwkv_consumer(const Params& p, const Ctx& cx, int l, int task, int lane, const char* ring, int widx) {
;   const int unit = task >> 4, d = unit & 1, h = (unit >> 1) & 15, b = unit >> 5;
;   const int j = lane >> 4, s = lane & 15;
;   const int myrow = (task & 15) * 4 + j;
;   char* pO = (char*)((h16*)(p.ws + OFF_REG2) + (size_t)d * ARR + h * 64);
;   const int sm = d ? 3 - (s & 3) : (s & 3);
;   const unsigned vov0 = (unsigned)(sm * 2048 + myrow * 2);
;   const unsigned rofs = (unsigned)(s * 8);
;   const unsigned vrofs = (unsigned)(2560 + myrow * 2);
;   LAS3 volatile int* pflag = (LAS3 volatile int*)(ring + RW_FLAGS);
;   LAS3 volatile int* cflag = (LAS3 volatile int*)(ring + RW_FLAGS + 64) + widx;
;   float S0 = 0.f, S1 = 0.f, S2 = 0.f, S3 = 0.f;
;   int pseen = 0;
;   struct GD { u2v w[4], kk[4], kka[4], kd[4], r[4]; unsigned v[4]; };
;   GD A, B;
.LBB0_229:
	s_ashr_i32 s4, s31, 4
	s_lshl_b32 s1, s34, 4
	s_and_b32 s4, s4, -4
	s_or_b32 s1, s1, s4
	s_or_b32 s4, s1, s50
	s_lshl_b32 s1, s4, 2
	v_and_or_b32 v0, s1, 60, v107
	s_waitcnt vmcnt(0)
	v_lshlrev_b32_e32 v82, 1, v0
	v_add_u32_e32 v0, 16, v116
	v_add_u32_e32 v36, 16, v117
	v_add_u32_e32 v20, 0x800, v0
	v_add_u32_e32 v41, 16, v82
	ds_read2_b64 v[0:3], v20 offset1:16
	ds_read_b128 v[4:7], v36
	ds_read_b128 v[8:11], v36 offset:256
	ds_read_b128 v[12:15], v36 offset:1024
	ds_read_b128 v[16:19], v36 offset:1280
	ds_read2_b64 v[20:23], v20 offset0:32 offset1:48
	ds_read_b128 v[24:27], v36 offset:512
	s_waitcnt vmcnt(9)
	ds_read_b128 v[28:31], v36 offset:768
	s_waitcnt vmcnt(3)
	ds_read_b128 v[32:35], v36 offset:1536
	ds_read_b128 v[36:39], v36 offset:1792
	ds_read_u16 v88, v41 offset:2560
	ds_read_u16 v89, v41 offset:2688
	ds_read_u16 v90, v41 offset:2816
	ds_read_u16 v91, v41 offset:2944
	s_bfe_u32 s5, s4, 0x10004
	s_mul_i32 s8, s5, 0x4100000
	s_add_u32 s8, s20, s8
	s_addc_u32 s10, s21, 0
	s_and_b32 s1, s1, 0x780
	s_add_u32 s1, s8, s1
	s_addc_u32 s8, s10, 0
	s_cmp_eq_u32 s5, 0
	s_cselect_b64 s[42:43], -1, 0
	s_ashr_i32 s4, s4, 9
	v_cndmask_b32_e64 v40, v115, v114, s[42:43]
	s_lshl_b32 s22, s4, 8
	s_mov_b32 s33, 0
	v_or_b32_e32 v83, v40, v82
	s_lshl_b32 s10, s4, 14
	s_add_i32 s22, s22, 0x8000
	v_mov_b32_e32 v84, 0
	v_mov_b32_e32 v85, 0
	v_mov_b32_e32 v86, 0
	v_mov_b32_e32 v87, 0
	s_waitcnt vmcnt(0)
	s_and_b64 s[4:5], s[42:43], exec
	s_cselect_b32 s4, 0, 0xfc
	s_add_i32 s4, s22, s4
	s_lshl_b32 s4, s4, 11
	s_add_u32 s36, s1, s4
	s_addc_u32 s37, s8, 0
	s_and_b64 s[4:5], s[42:43], exec
	s_cselect_b32 s4, 0, 0x3ffc
	s_add_i32 s4, s10, s4
	s_lshl_b32 s4, s4, 11
	s_add_u32 s88, s1, s4
	s_addc_u32 s89, s8, 0
	s_and_b64 s[4:5], s[42:43], exec
	s_mov_b32 s44, 0xffffe000
	s_and_b64 s[4:5], s[42:43], exec
	s_cselect_b32 s44, 0x2000, s44
	s_cselect_b32 s45, 0, -1
	v_mov_b32_e32 v172, s9
	v_add_u32_e32 v177, 0x800, v116
	s_movk_i32 s4, 0xc10
	v_add_u32_e32 v178, s4, v177
	v_add_u32_e32 v179, s4, v117
	v_add_u32_e32 v180, s4, v82
	s_branch .Lc_top
.Lc_top:
	s_add_i32 s23, s33, 1
	s_cmp_gt_i32 s0, s23
	s_cbranch_scc0 .Lc_poll1
.Lc_h1:
	ds_read2_b64 v[56:59], v178 offset1:16
	ds_read_b128 v[72:75], v179
	ds_read_b128 v[64:67], v179 offset:256
	ds_read_b128 v[76:79], v179 offset:1024
	ds_read_b128 v[68:71], v179 offset:1280
	ds_read2_b64 v[40:43], v178 offset0:32 offset1:48
	ds_read_b128 v[52:55], v179 offset:512
	ds_read_b128 v[44:47], v179 offset:768
	ds_read_b128 v[60:63], v179 offset:1536
	ds_read_b128 v[48:51], v179 offset:1792
	ds_read_u16 v92, v180 offset:2560
	s_waitcnt lgkmcnt(11)
	v_fma_mix_f32 v98, v84, v6, 0 op_sel:[0,0,0] op_sel_hi:[0,1,0]
	ds_read_u16 v93, v180 offset:2688
	v_fma_mix_f32 v98, v85, v6, v98 op_sel:[0,1,0] op_sel_hi:[0,1,0]
	ds_read_u16 v94, v180 offset:2816
	v_fma_mix_f32 v98, v86, v7, v98 op_sel:[0,0,0] op_sel_hi:[0,1,0]
	ds_read_u16 v95, v180 offset:2944
	v_fma_mix_f32 v98, v87, v7, v98 op_sel:[0,1,0] op_sel_hi:[0,1,0]
	v_fma_mix_f32 v100, v88, v14, 0 op_sel:[0,0,0] op_sel_hi:[1,1,0]
	v_fma_mix_f32 v101, v88, v14, 0 op_sel:[0,1,0] op_sel_hi:[1,1,0]
	v_add_f32_dpp v98, v98, v98 quad_perm:[1,0,3,2] row_mask:0xf bank_mask:0xf bound_ctrl:1
	v_fma_mix_f32 v102, v88, v15, 0 op_sel:[0,0,0] op_sel_hi:[1,1,0]
	v_fma_mix_f32 v103, v88, v15, 0 op_sel:[0,1,0] op_sel_hi:[1,1,0]
	v_add_f32_dpp v98, v98, v98 quad_perm:[2,3,0,1] row_mask:0xf bank_mask:0xf bound_ctrl:1
	v_fma_mix_f32 v84, v84, v4, v100 op_sel:[0,0,0] op_sel_hi:[0,1,0]
	v_fma_mix_f32 v85, v85, v4, v101 op_sel:[0,1,0] op_sel_hi:[0,1,0]
	v_add_f32_dpp v98, v98, v98 row_half_mirror row_mask:0xf bank_mask:0xf bound_ctrl:1
	v_fma_mix_f32 v86, v86, v5, v102 op_sel:[0,0,0] op_sel_hi:[0,1,0]
	v_fma_mix_f32 v87, v87, v5, v103 op_sel:[0,1,0] op_sel_hi:[0,1,0]
	v_add_f32_dpp v98, v98, v98 row_mirror row_mask:0xf bank_mask:0xf bound_ctrl:1
	v_fma_mix_f32 v84, -v98, v12, v84 op_sel:[0,0,0] op_sel_hi:[0,1,0]
	v_fma_mix_f32 v85, -v98, v12, v85 op_sel:[0,1,0] op_sel_hi:[0,1,0]
	v_fma_mix_f32 v86, -v98, v13, v86 op_sel:[0,0,0] op_sel_hi:[0,1,0]
	v_fma_mix_f32 v87, -v98, v13, v87 op_sel:[0,1,0] op_sel_hi:[0,1,0]
	v_fma_mix_f32 v99, v84, v10, 0 op_sel:[0,0,0] op_sel_hi:[0,1,0]
	v_fma_mix_f32 v96, v84, v0, 0 op_sel:[0,0,0] op_sel_hi:[0,1,0]
	v_fma_mix_f32 v99, v85, v10, v99 op_sel:[0,1,0] op_sel_hi:[0,1,0]
	v_fma_mix_f32 v96, v85, v0, v96 op_sel:[0,1,0] op_sel_hi:[0,1,0]
	v_fma_mix_f32 v99, v86, v11, v99 op_sel:[0,0,0] op_sel_hi:[0,1,0]
	v_fma_mix_f32 v96, v86, v1, v96 op_sel:[0,0,0] op_sel_hi:[0,1,0]
	v_fma_mix_f32 v99, v87, v11, v99 op_sel:[0,1,0] op_sel_hi:[0,1,0]
	v_fma_mix_f32 v96, v87, v1, v96 op_sel:[0,1,0] op_sel_hi:[0,1,0]
	v_fma_mix_f32 v101, v89, v18, 0 op_sel:[0,0,0] op_sel_hi:[1,1,0]
	v_fma_mix_f32 v102, v89, v18, 0 op_sel:[0,1,0] op_sel_hi:[1,1,0]
	v_add_f32_dpp v99, v99, v99 quad_perm:[1,0,3,2] row_mask:0xf bank_mask:0xf bound_ctrl:1
	v_fma_mix_f32 v103, v89, v19, 0 op_sel:[0,0,0] op_sel_hi:[1,1,0]
	v_fma_mix_f32 v104, v89, v19, 0 op_sel:[0,1,0] op_sel_hi:[1,1,0]
	v_add_f32_dpp v99, v99, v99 quad_perm:[2,3,0,1] row_mask:0xf bank_mask:0xf bound_ctrl:1
	v_fma_mix_f32 v84, v84, v8, v101 op_sel:[0,0,0] op_sel_hi:[0,1,0]
	v_fma_mix_f32 v85, v85, v8, v102 op_sel:[0,1,0] op_sel_hi:[0,1,0]
	v_add_f32_dpp v99, v99, v99 row_half_mirror row_mask:0xf bank_mask:0xf bound_ctrl:1
	v_fma_mix_f32 v86, v86, v9, v103 op_sel:[0,0,0] op_sel_hi:[0,1,0]
	v_fma_mix_f32 v87, v87, v9, v104 op_sel:[0,1,0] op_sel_hi:[0,1,0]
	v_add_f32_dpp v99, v99, v99 row_mirror row_mask:0xf bank_mask:0xf bound_ctrl:1
	v_fma_mix_f32 v84, -v99, v16, v84 op_sel:[0,0,0] op_sel_hi:[0,1,0]
; #define RC_WAIT(gq) { if (pseen <= (gq)) { do { pseen = __builtin_amdgcn_readfirstlane(*pflag); if (pseen <= (gq)) __builtin_amdgcn_s_sleep(1); } while (pseen <= (gq)); } asm volatile("" ::: "memory"); }
; DEV void rwkv_consumer(const Params& p, const Ctx& cx, int l, int task, int lane, const char* ring, int widx) {
;     ...
;   RC_WAIT(0); RC_LOAD(A, 0);
; #pragma unroll 1
;   for (int g = 0; g < RW_NG; g += 2) {
;     RC_WAIT(g + 1); RC_LOAD(B, g + 1);
;     RC_COMP(A, g);
;     if (g + 2 < RW_NG) { RC_WAIT(g + 2); RC_LOAD(A, g + 2); }
	v_fma_mix_f32 v85, -v99, v16, v85 op_sel:[0,1,0] op_sel_hi:[0,1,0]
	v_fma_mix_f32 v86, -v99, v17, v86 op_sel:[0,0,0] op_sel_hi:[0,1,0]
	v_fma_mix_f32 v87, -v99, v17, v87 op_sel:[0,1,0] op_sel_hi:[0,1,0]
	v_fma_mix_f32 v100, v84, v26, 0 op_sel:[0,0,0] op_sel_hi:[0,1,0]
	v_fma_mix_f32 v97, v84, v2, 0 op_sel:[0,0,0] op_sel_hi:[0,1,0]
	v_fma_mix_f32 v100, v85, v26, v100 op_sel:[0,1,0] op_sel_hi:[0,1,0]
	v_fma_mix_f32 v97, v85, v2, v97 op_sel:[0,1,0] op_sel_hi:[0,1,0]
	v_fma_mix_f32 v100, v86, v27, v100 op_sel:[0,0,0] op_sel_hi:[0,1,0]
	v_fma_mix_f32 v97, v86, v3, v97 op_sel:[0,0,0] op_sel_hi:[0,1,0]
	v_fma_mix_f32 v100, v87, v27, v100 op_sel:[0,1,0] op_sel_hi:[0,1,0]
	v_fma_mix_f32 v97, v87, v3, v97 op_sel:[0,1,0] op_sel_hi:[0,1,0]
	v_fma_mix_f32 v102, v90, v34, 0 op_sel:[0,0,0] op_sel_hi:[1,1,0]
	v_fma_mix_f32 v103, v90, v34, 0 op_sel:[0,1,0] op_sel_hi:[1,1,0]
	v_add_f32_dpp v100, v100, v100 quad_perm:[1,0,3,2] row_mask:0xf bank_mask:0xf bound_ctrl:1
	v_fma_mix_f32 v104, v90, v35, 0 op_sel:[0,0,0] op_sel_hi:[1,1,0]
	v_fma_mix_f32 v105, v90, v35, 0 op_sel:[0,1,0] op_sel_hi:[1,1,0]
	v_add_f32_dpp v100, v100, v100 quad_perm:[2,3,0,1] row_mask:0xf bank_mask:0xf bound_ctrl:1
	v_fma_mix_f32 v84, v84, v24, v102 op_sel:[0,0,0] op_sel_hi:[0,1,0]
	v_fma_mix_f32 v85, v85, v24, v103 op_sel:[0,1,0] op_sel_hi:[0,1,0]
	v_add_f32_dpp v100, v100, v100 row_half_mirror row_mask:0xf bank_mask:0xf bound_ctrl:1
	v_fma_mix_f32 v86, v86, v25, v104 op_sel:[0,0,0] op_sel_hi:[0,1,0]
	v_fma_mix_f32 v87, v87, v25, v105 op_sel:[0,1,0] op_sel_hi:[0,1,0]
	v_add_f32_dpp v100, v100, v100 row_mirror row_mask:0xf bank_mask:0xf bound_ctrl:1
	v_fma_mix_f32 v84, -v100, v32, v84 op_sel:[0,0,0] op_sel_hi:[0,1,0]
	v_fma_mix_f32 v85, -v100, v32, v85 op_sel:[0,1,0] op_sel_hi:[0,1,0]
	v_fma_mix_f32 v86, -v100, v33, v86 op_sel:[0,0,0] op_sel_hi:[0,1,0]
	v_fma_mix_f32 v87, -v100, v33, v87 op_sel:[0,1,0] op_sel_hi:[0,1,0]
	v_fma_mix_f32 v101, v84, v30, 0 op_sel:[0,0,0] op_sel_hi:[0,1,0]
	v_fma_mix_f32 v98, v84, v20, 0 op_sel:[0,0,0] op_sel_hi:[0,1,0]
	v_fma_mix_f32 v101, v85, v30, v101 op_sel:[0,1,0] op_sel_hi:[0,1,0]
	v_fma_mix_f32 v98, v85, v20, v98 op_sel:[0,1,0] op_sel_hi:[0,1,0]
	v_fma_mix_f32 v101, v86, v31, v101 op_sel:[0,0,0] op_sel_hi:[0,1,0]
	v_fma_mix_f32 v98, v86, v21, v98 op_sel:[0,0,0] op_sel_hi:[0,1,0]
	v_fma_mix_f32 v101, v87, v31, v101 op_sel:[0,1,0] op_sel_hi:[0,1,0]
	v_fma_mix_f32 v98, v87, v21, v98 op_sel:[0,1,0] op_sel_hi:[0,1,0]
	v_fma_mix_f32 v103, v91, v38, 0 op_sel:[0,0,0] op_sel_hi:[1,1,0]
	v_fma_mix_f32 v104, v91, v38, 0 op_sel:[0,1,0] op_sel_hi:[1,1,0]
	v_add_f32_dpp v101, v101, v101 quad_perm:[1,0,3,2] row_mask:0xf bank_mask:0xf bound_ctrl:1
	v_fma_mix_f32 v105, v91, v39, 0 op_sel:[0,0,0] op_sel_hi:[1,1,0]
	v_fma_mix_f32 v119, v91, v39, 0 op_sel:[0,1,0] op_sel_hi:[1,1,0]
	v_add_f32_dpp v101, v101, v101 quad_perm:[2,3,0,1] row_mask:0xf bank_mask:0xf bound_ctrl:1
	v_fma_mix_f32 v84, v84, v28, v103 op_sel:[0,0,0] op_sel_hi:[0,1,0]
	v_fma_mix_f32 v85, v85, v28, v104 op_sel:[0,1,0] op_sel_hi:[0,1,0]
	v_add_f32_dpp v101, v101, v101 row_half_mirror row_mask:0xf bank_mask:0xf bound_ctrl:1
	v_fma_mix_f32 v86, v86, v29, v105 op_sel:[0,0,0] op_sel_hi:[0,1,0]
	v_fma_mix_f32 v87, v87, v29, v119 op_sel:[0,1,0] op_sel_hi:[0,1,0]
	v_add_f32_dpp v101, v101, v101 row_mirror row_mask:0xf bank_mask:0xf bound_ctrl:1
	v_fma_mix_f32 v84, -v101, v36, v84 op_sel:[0,0,0] op_sel_hi:[0,1,0]
	v_fma_mix_f32 v85, -v101, v36, v85 op_sel:[0,1,0] op_sel_hi:[0,1,0]
	v_fma_mix_f32 v86, -v101, v37, v86 op_sel:[0,0,0] op_sel_hi:[0,1,0]
	v_fma_mix_f32 v87, -v101, v37, v87 op_sel:[0,1,0] op_sel_hi:[0,1,0]
	v_fma_mix_f32 v99, v84, v22, 0 op_sel:[0,0,0] op_sel_hi:[0,1,0]
	v_fma_mix_f32 v99, v85, v22, v99 op_sel:[0,1,0] op_sel_hi:[0,1,0]
	v_fma_mix_f32 v99, v86, v23, v99 op_sel:[0,0,0] op_sel_hi:[0,1,0]
	v_fma_mix_f32 v99, v87, v23, v99 op_sel:[0,1,0] op_sel_hi:[0,1,0]
	v_cndmask_b32_e64 v101, v97, v96, s[38:39]
	v_cndmask_b32_e64 v96, v96, v97, s[38:39]
	v_cndmask_b32_e64 v97, v99, v98, s[38:39]
	v_cndmask_b32_e64 v98, v98, v99, s[38:39]
	s_add_i32 s34, s33, 2
	v_add_f32_dpp v96, v96, v101 quad_perm:[1,0,3,2] row_mask:0xf bank_mask:0xf bound_ctrl:1
	s_and_b32 s4, s34, 14
	s_mulk_i32 s4, 0xc00
	v_add_f32_dpp v97, v98, v97 quad_perm:[1,0,3,2] row_mask:0xf bank_mask:0xf bound_ctrl:1
	s_add_i32 s4, s4, 16
	v_cndmask_b32_e64 v98, v97, v96, s[40:41]
	v_cndmask_b32_e64 v96, v96, v97, s[40:41]
	v_add_u32_e32 v174, s4, v177
	v_add_u32_e32 v175, s4, v117
	v_add_f32_dpp v96, v96, v98 quad_perm:[2,3,0,1] row_mask:0xf bank_mask:0xf bound_ctrl:1
	v_add_u32_e32 v176, s4, v82
	v_mov_b32_e32 v173, s23
	v_add_f32_dpp v96, v96, v96 row_ror:4 row_mask:0xf bank_mask:0xf bound_ctrl:1
	ds_write_b32 v172, v173 offset:49216
	s_nop 0
	v_add_f32_dpp v96, v96, v96 row_ror:8 row_mask:0xf bank_mask:0xf bound_ctrl:1
	v_cvt_f16_f32_e32 v96, v96
	global_store_short v83, v96, s[36:37]
	s_add_u32 s36, s36, s44
	s_addc_u32 s37, s37, s45
	s_cmpk_gt_u32 s33, 0x103d
	s_cbranch_scc1 .Lc_last
	s_cmp_gt_i32 s0, s34
	s_cbranch_scc0 .Lc_poll2
.Lc_ld2:
	ds_read2_b64 v[0:3], v174 offset1:16
	ds_read_b128 v[4:7], v175
	ds_read_b128 v[8:11], v175 offset:256
	ds_read_b128 v[12:15], v175 offset:1024
	ds_read_b128 v[16:19], v175 offset:1280
	ds_read2_b64 v[20:23], v174 offset0:32 offset1:48
	ds_read_b128 v[24:27], v175 offset:512
	ds_read_b128 v[28:31], v175 offset:768
	ds_read_b128 v[32:35], v175 offset:1536
	ds_read_b128 v[36:39], v175 offset:1792
	ds_read_u16 v88, v176 offset:2560
	ds_read_u16 v89, v176 offset:2688
	ds_read_u16 v90, v176 offset:2816
	ds_read_u16 v91, v176 offset:2944
	s_waitcnt lgkmcnt(14)
.Lc_h2:
	v_fma_mix_f32 v98, v84, v74, 0 op_sel:[0,0,0] op_sel_hi:[0,1,0]
	v_fma_mix_f32 v98, v85, v74, v98 op_sel:[0,1,0] op_sel_hi:[0,1,0]
	v_fma_mix_f32 v98, v86, v75, v98 op_sel:[0,0,0] op_sel_hi:[0,1,0]
	v_fma_mix_f32 v98, v87, v75, v98 op_sel:[0,1,0] op_sel_hi:[0,1,0]
	v_fma_mix_f32 v100, v92, v78, 0 op_sel:[0,0,0] op_sel_hi:[1,1,0]
	v_fma_mix_f32 v101, v92, v78, 0 op_sel:[0,1,0] op_sel_hi:[1,1,0]
	v_add_f32_dpp v98, v98, v98 quad_perm:[1,0,3,2] row_mask:0xf bank_mask:0xf bound_ctrl:1
	v_fma_mix_f32 v102, v92, v79, 0 op_sel:[0,0,0] op_sel_hi:[1,1,0]
	v_fma_mix_f32 v103, v92, v79, 0 op_sel:[0,1,0] op_sel_hi:[1,1,0]
	v_add_f32_dpp v98, v98, v98 quad_perm:[2,3,0,1] row_mask:0xf bank_mask:0xf bound_ctrl:1
	v_fma_mix_f32 v84, v84, v72, v100 op_sel:[0,0,0] op_sel_hi:[0,1,0]
	v_fma_mix_f32 v85, v85, v72, v101 op_sel:[0,1,0] op_sel_hi:[0,1,0]
	v_add_f32_dpp v98, v98, v98 row_half_mirror row_mask:0xf bank_mask:0xf bound_ctrl:1
	v_fma_mix_f32 v86, v86, v73, v102 op_sel:[0,0,0] op_sel_hi:[0,1,0]
	v_fma_mix_f32 v87, v87, v73, v103 op_sel:[0,1,0] op_sel_hi:[0,1,0]
	v_add_f32_dpp v98, v98, v98 row_mirror row_mask:0xf bank_mask:0xf bound_ctrl:1
	v_fma_mix_f32 v84, -v98, v76, v84 op_sel:[0,0,0] op_sel_hi:[0,1,0]
	v_fma_mix_f32 v85, -v98, v76, v85 op_sel:[0,1,0] op_sel_hi:[0,1,0]
	v_fma_mix_f32 v86, -v98, v77, v86 op_sel:[0,0,0] op_sel_hi:[0,1,0]
	v_fma_mix_f32 v87, -v98, v77, v87 op_sel:[0,1,0] op_sel_hi:[0,1,0]
	v_fma_mix_f32 v73, v84, v66, 0 op_sel:[0,0,0] op_sel_hi:[0,1,0]
	v_fma_mix_f32 v97, v84, v56, 0 op_sel:[0,0,0] op_sel_hi:[0,1,0]
	v_fma_mix_f32 v73, v85, v66, v73 op_sel:[0,1,0] op_sel_hi:[0,1,0]
	v_fma_mix_f32 v56, v85, v56, v97 op_sel:[0,1,0] op_sel_hi:[0,1,0]
	v_fma_mix_f32 v73, v86, v67, v73 op_sel:[0,0,0] op_sel_hi:[0,1,0]
	v_fma_mix_f32 v56, v86, v57, v56 op_sel:[0,0,0] op_sel_hi:[0,1,0]
	v_fma_mix_f32 v73, v87, v67, v73 op_sel:[0,1,0] op_sel_hi:[0,1,0]
	v_fma_mix_f32 v56, v87, v57, v56 op_sel:[0,1,0] op_sel_hi:[0,1,0]
	v_fma_mix_f32 v75, v93, v70, 0 op_sel:[0,0,0] op_sel_hi:[1,1,0]
	v_fma_mix_f32 v76, v93, v70, 0 op_sel:[0,1,0] op_sel_hi:[1,1,0]
	v_add_f32_dpp v73, v73, v73 quad_perm:[1,0,3,2] row_mask:0xf bank_mask:0xf bound_ctrl:1
	v_fma_mix_f32 v77, v93, v71, 0 op_sel:[0,0,0] op_sel_hi:[1,1,0]
	v_fma_mix_f32 v78, v93, v71, 0 op_sel:[0,1,0] op_sel_hi:[1,1,0]
	v_add_f32_dpp v73, v73, v73 quad_perm:[2,3,0,1] row_mask:0xf bank_mask:0xf bound_ctrl:1
	v_fma_mix_f32 v84, v84, v64, v75 op_sel:[0,0,0] op_sel_hi:[0,1,0]
	v_fma_mix_f32 v85, v85, v64, v76 op_sel:[0,1,0] op_sel_hi:[0,1,0]
	v_add_f32_dpp v73, v73, v73 row_half_mirror row_mask:0xf bank_mask:0xf bound_ctrl:1
	v_fma_mix_f32 v86, v86, v65, v77 op_sel:[0,0,0] op_sel_hi:[0,1,0]
	v_fma_mix_f32 v87, v87, v65, v78 op_sel:[0,1,0] op_sel_hi:[0,1,0]
	v_add_f32_dpp v73, v73, v73 row_mirror row_mask:0xf bank_mask:0xf bound_ctrl:1
	v_fma_mix_f32 v84, -v73, v68, v84 op_sel:[0,0,0] op_sel_hi:[0,1,0]
	v_fma_mix_f32 v85, -v73, v68, v85 op_sel:[0,1,0] op_sel_hi:[0,1,0]
	v_fma_mix_f32 v86, -v73, v69, v86 op_sel:[0,0,0] op_sel_hi:[0,1,0]
	v_fma_mix_f32 v87, -v73, v69, v87 op_sel:[0,1,0] op_sel_hi:[0,1,0]
	v_fma_mix_f32 v64, v84, v54, 0 op_sel:[0,0,0] op_sel_hi:[0,1,0]
	v_fma_mix_f32 v57, v84, v58, 0 op_sel:[0,0,0] op_sel_hi:[0,1,0]
	v_fma_mix_f32 v64, v85, v54, v64 op_sel:[0,1,0] op_sel_hi:[0,1,0]
	v_fma_mix_f32 v57, v85, v58, v57 op_sel:[0,1,0] op_sel_hi:[0,1,0]
	v_fma_mix_f32 v64, v86, v55, v64 op_sel:[0,0,0] op_sel_hi:[0,1,0]
	v_fma_mix_f32 v57, v86, v59, v57 op_sel:[0,0,0] op_sel_hi:[0,1,0]
	v_fma_mix_f32 v64, v87, v55, v64 op_sel:[0,1,0] op_sel_hi:[0,1,0]
	v_fma_mix_f32 v57, v87, v59, v57 op_sel:[0,1,0] op_sel_hi:[0,1,0]
	v_fma_mix_f32 v66, v94, v62, 0 op_sel:[0,0,0] op_sel_hi:[1,1,0]
	v_fma_mix_f32 v67, v94, v62, 0 op_sel:[0,1,0] op_sel_hi:[1,1,0]
	v_add_f32_dpp v64, v64, v64 quad_perm:[1,0,3,2] row_mask:0xf bank_mask:0xf bound_ctrl:1
	v_fma_mix_f32 v68, v94, v63, 0 op_sel:[0,0,0] op_sel_hi:[1,1,0]
	v_fma_mix_f32 v69, v94, v63, 0 op_sel:[0,1,0] op_sel_hi:[1,1,0]
	v_add_f32_dpp v64, v64, v64 quad_perm:[2,3,0,1] row_mask:0xf bank_mask:0xf bound_ctrl:1
	v_fma_mix_f32 v84, v84, v52, v66 op_sel:[0,0,0] op_sel_hi:[0,1,0]
	v_fma_mix_f32 v85, v85, v52, v67 op_sel:[0,1,0] op_sel_hi:[0,1,0]
; #define RC_WAIT(gq) { if (pseen <= (gq)) { do { pseen = __builtin_amdgcn_readfirstlane(*pflag); if (pseen <= (gq)) __builtin_amdgcn_s_sleep(1); } while (pseen <= (gq)); } asm volatile("" ::: "memory"); }
; DEV void rwkv_consumer(const Params& p, const Ctx& cx, int l, int task, int lane, const char* ring, int widx) {
;     ...
;   RC_WAIT(0); RC_LOAD(A, 0);
; #pragma unroll 1
;   for (int g = 0; g < RW_NG; g += 2) {
;     RC_WAIT(g + 1); RC_LOAD(B, g + 1);
;     RC_COMP(A, g);
;     if (g + 2 < RW_NG) { RC_WAIT(g + 2); RC_LOAD(A, g + 2); }
;     RC_COMP(B, g + 1);
;   }
	v_add_f32_dpp v64, v64, v64 row_half_mirror row_mask:0xf bank_mask:0xf bound_ctrl:1
	v_fma_mix_f32 v86, v86, v53, v68 op_sel:[0,0,0] op_sel_hi:[0,1,0]
	v_fma_mix_f32 v87, v87, v53, v69 op_sel:[0,1,0] op_sel_hi:[0,1,0]
	v_add_f32_dpp v64, v64, v64 row_mirror row_mask:0xf bank_mask:0xf bound_ctrl:1
	v_fma_mix_f32 v84, -v64, v60, v84 op_sel:[0,0,0] op_sel_hi:[0,1,0]
	v_fma_mix_f32 v85, -v64, v60, v85 op_sel:[0,1,0] op_sel_hi:[0,1,0]
	v_fma_mix_f32 v86, -v64, v61, v86 op_sel:[0,0,0] op_sel_hi:[0,1,0]
	v_fma_mix_f32 v87, -v64, v61, v87 op_sel:[0,1,0] op_sel_hi:[0,1,0]
	v_fma_mix_f32 v53, v84, v46, 0 op_sel:[0,0,0] op_sel_hi:[0,1,0]
	v_fma_mix_f32 v59, v84, v40, 0 op_sel:[0,0,0] op_sel_hi:[0,1,0]
	v_fma_mix_f32 v53, v85, v46, v53 op_sel:[0,1,0] op_sel_hi:[0,1,0]
	v_fma_mix_f32 v40, v85, v40, v59 op_sel:[0,1,0] op_sel_hi:[0,1,0]
	v_fma_mix_f32 v53, v86, v47, v53 op_sel:[0,0,0] op_sel_hi:[0,1,0]
	v_fma_mix_f32 v40, v86, v41, v40 op_sel:[0,0,0] op_sel_hi:[0,1,0]
	v_fma_mix_f32 v53, v87, v47, v53 op_sel:[0,1,0] op_sel_hi:[0,1,0]
	v_fma_mix_f32 v40, v87, v41, v40 op_sel:[0,1,0] op_sel_hi:[0,1,0]
	v_fma_mix_f32 v55, v95, v50, 0 op_sel:[0,0,0] op_sel_hi:[1,1,0]
	v_fma_mix_f32 v58, v95, v50, 0 op_sel:[0,1,0] op_sel_hi:[1,1,0]
	v_add_f32_dpp v53, v53, v53 quad_perm:[1,0,3,2] row_mask:0xf bank_mask:0xf bound_ctrl:1
	v_fma_mix_f32 v59, v95, v51, 0 op_sel:[0,0,0] op_sel_hi:[1,1,0]
	v_fma_mix_f32 v60, v95, v51, 0 op_sel:[0,1,0] op_sel_hi:[1,1,0]
	v_add_f32_dpp v53, v53, v53 quad_perm:[2,3,0,1] row_mask:0xf bank_mask:0xf bound_ctrl:1
	v_fma_mix_f32 v84, v84, v44, v55 op_sel:[0,0,0] op_sel_hi:[0,1,0]
	v_fma_mix_f32 v85, v85, v44, v58 op_sel:[0,1,0] op_sel_hi:[0,1,0]
	v_add_f32_dpp v53, v53, v53 row_half_mirror row_mask:0xf bank_mask:0xf bound_ctrl:1
	v_fma_mix_f32 v86, v86, v45, v59 op_sel:[0,0,0] op_sel_hi:[0,1,0]
	v_fma_mix_f32 v87, v87, v45, v60 op_sel:[0,1,0] op_sel_hi:[0,1,0]
	v_add_f32_dpp v53, v53, v53 row_mirror row_mask:0xf bank_mask:0xf bound_ctrl:1
	v_fma_mix_f32 v84, -v53, v48, v84 op_sel:[0,0,0] op_sel_hi:[0,1,0]
	v_fma_mix_f32 v85, -v53, v48, v85 op_sel:[0,1,0] op_sel_hi:[0,1,0]
	v_fma_mix_f32 v86, -v53, v49, v86 op_sel:[0,0,0] op_sel_hi:[0,1,0]
	v_fma_mix_f32 v87, -v53, v49, v87 op_sel:[0,1,0] op_sel_hi:[0,1,0]
	v_fma_mix_f32 v41, v84, v42, 0 op_sel:[0,0,0] op_sel_hi:[0,1,0]
	v_fma_mix_f32 v41, v85, v42, v41 op_sel:[0,1,0] op_sel_hi:[0,1,0]
	v_fma_mix_f32 v41, v86, v43, v41 op_sel:[0,0,0] op_sel_hi:[0,1,0]
	v_fma_mix_f32 v41, v87, v43, v41 op_sel:[0,1,0] op_sel_hi:[0,1,0]
	v_cndmask_b32_e64 v43, v57, v56, s[38:39]
	v_cndmask_b32_e64 v44, v56, v57, s[38:39]
	s_add_i32 s4, s33, 3
	s_mov_b32 s33, s34
	v_add_f32_dpp v43, v44, v43 quad_perm:[1,0,3,2] row_mask:0xf bank_mask:0xf bound_ctrl:1
	v_cndmask_b32_e64 v44, v41, v40, s[38:39]
	v_cndmask_b32_e64 v40, v40, v41, s[38:39]
	s_and_b32 s4, s4, 15
	s_mulk_i32 s4, 0xc00
	v_add_f32_dpp v40, v40, v44 quad_perm:[1,0,3,2] row_mask:0xf bank_mask:0xf bound_ctrl:1
	v_cndmask_b32_e64 v41, v40, v43, s[40:41]
	v_cndmask_b32_e64 v40, v43, v40, s[40:41]
	s_add_i32 s4, s4, 16
	v_add_u32_e32 v178, s4, v177
	v_add_f32_dpp v40, v40, v41 quad_perm:[2,3,0,1] row_mask:0xf bank_mask:0xf bound_ctrl:1
	v_add_u32_e32 v179, s4, v117
	v_add_u32_e32 v180, s4, v82
	v_add_f32_dpp v40, v40, v40 row_ror:4 row_mask:0xf bank_mask:0xf bound_ctrl:1
	v_mov_b32_e32 v173, s34
	ds_write_b32 v172, v173 offset:49216
	v_add_f32_dpp v40, v40, v40 row_ror:8 row_mask:0xf bank_mask:0xf bound_ctrl:1
	v_cvt_f16_f32_e32 v40, v40
	global_store_short v83, v40, s[36:37]
	s_add_u32 s36, s36, s44
	s_addc_u32 s37, s37, s45
	s_cmp_eq_u32 s34, 64
	s_cbranch_scc1 .Lc_fix
.Lc_fixret:
	s_cmpk_lt_u32 s33, 0x1040
	s_cbranch_scc1 .Lc_top
	s_branch .LBB0_241
.Lc_fix:
	s_mov_b64 s[36:37], s[88:89]
	s_branch .Lc_fixret
.Lc_last:
	s_waitcnt lgkmcnt(0)
	s_branch .Lc_h2
.Lc_poll1:
	ds_read_b32 v173, v161 offset:49152
	s_waitcnt lgkmcnt(0)
	v_readfirstlane_b32 s0, v173
	s_cmp_gt_i32 s0, s23
	s_cbranch_scc1 .Lc_h1
	s_sleep 1
	s_branch .Lc_poll1
.Lc_poll2:
	ds_read_b32 v173, v161 offset:49152
	s_waitcnt lgkmcnt(0)
	v_readfirstlane_b32 s0, v173
	s_cmp_gt_i32 s0, s34
	s_cbranch_scc1 .Lc_ld2
	s_sleep 1
	s_branch .Lc_poll2
